# adds: nt (streaming) cache policy on the read-once attention Q/K/V row loads
# speedup vs baseline: 1.0104x; 1.0104x over previous
; #define LAS __attribute__((address_space(3)))
; DI void attn_phase(LAS unsigned char* lds, bf16_t* QKV, float* LSE, const float* qg, const float* kg, const float* relb, int G, int bid) {
;     ...
;     const int per = (6144 + G - 1) / G; const int u0 = bid * per; int u1 = u0 + per; if (u1 > 6144) u1 = 6144;
;     const int kp2 = tid & 63, vpc = tid >> 6;
;     u32x4 pq[2], pk[2], pv[2];
;     int rn, h, g, d, n; size_t rowbase;
;     if (u0 < u1) { attn_unit_ptrs(u0, rn, h, g, d, n, rowbase);
;         const bf16_t* qp = QKV + (size_t)g * SEC + rowbase * 1024 + h * 64; const bf16_t* kp = qp + 3 * SEC; const bf16_t* vp = qp + 6 * SEC;
; #pragma unroll
;         for (int it = 0; it < 2; ++it) { const int idx = tid + 512 * it, row = idx >> 3, pc = idx & 7; pq[it] = *(const u32x4*)(qp + (size_t)row * 1024 + pc * 8); pk[it] = *(const u32x4*)(kp + (size_t)row * 1024 + pc * 8); }
;         pv[0] = *(const u32x4*)(vp + (size_t)(2 * kp2) * 1024 + vpc * 8); pv[1] = *(const u32x4*)(vp + (size_t)(2 * kp2 + 1) * 1024 + vpc * 8); }
;     ...
;         for (int i = 0; i < 9; ++i) { const int tau = w + i; const int kr = ((((n + 1 + (tau >> 3)) & 1) << 7) | ((tau & 7) << 4)) + fr; f32x4 acc = (f32x4){0.f, 0.f, 0.f, 0.f};
;             const bf16x8 a0 = *(const LAS bf16x8*)(Ks + kr * 72 + 8 * fq), a1 = *(const LAS bf16x8*)(Ks + kr * 72 + 32 + 8 * fq);
;             acc = __builtin_amdgcn_mfma_f32_16x16x32_bf16(a0, qf[0], acc, 0, 0, 0);
;             acc = __builtin_amdgcn_mfma_f32_16x16x32_bf16(a1, qf[1], acc, 0, 0, 0);
;             sc[i] = acc; }
;         float mx = -INFINITY;
;         const LAS float* tb = tab + (16 + fr - 4 * fq - 3);
;         const int dlt = fr - 4 * fq;
;         float bv[9][4];
; #pragma unroll
;         for (int i = 0; i < 9; ++i)
; #pragma unroll
;             for (int j = 0; j < 4; ++j) bv[i][j] = tb[16 * (8 - i) + (3 - j)];
.LBB0_310:
	s_cmp_gt_i32 s34, 1
	s_mov_b64 s[0:1], -1
	s_cbranch_scc0 .LBB0_331
	v_readlane_b32 s0, v251, 25
	v_readlane_b32 s1, v251, 26
	v_mov_b32_e32 v52, v226
	s_andn2_b64 vcc, exec, s[0:1]
	v_readlane_b32 s2, v251, 28
	s_cbranch_vccnz .LBB0_330
	s_waitcnt vmcnt(0)
	v_lshlrev_b32_e32 v0, 3, v52
	v_and_b32_e32 v24, 56, v0
	v_readlane_b32 s0, v251, 31
	v_lshlrev_b32_e32 v112, 1, v24
	v_readlane_b32 s1, v251, 32
	v_add_u32_e32 v41, 0x200, v52
	v_and_b32_e32 v39, 63, v52
	v_lshl_add_u64 v[8:9], s[0:1], 0, v[112:113]
	v_readlane_b32 s0, v251, 29
	v_readlane_b32 s1, v251, 30
	v_ashrrev_i32_e32 v71, 6, v52
	v_lshrrev_b32_e32 v122, 3, v39
	v_and_b32_e32 v123, 7, v52
	v_lshl_add_u32 v122, v71, 3, v122
	v_ashrrev_i32_e32 v26, 3, v52
	v_lshl_add_u64 v[10:11], s[0:1], 0, v[112:113]
	v_ashrrev_i32_e32 v30, 3, v41
	v_readlane_b32 s0, v251, 33
	v_ashrrev_i32_e32 v27, 31, v26
	v_ashrrev_i32_e32 v31, 31, v30
	v_lshlrev_b32_e32 v16, 12, v122
	v_mov_b32_e32 v17, v113
	v_readlane_b32 s1, v251, 34
	v_lshlrev_b32_e32 v36, 3, v123
	v_lshlrev_b64 v[28:29], 11, v[26:27]
	v_lshlrev_b64 v[32:33], 11, v[30:31]
	v_lshl_add_u64 v[16:17], s[0:1], 0, v[16:17]
	v_ashrrev_i32_e32 v37, 31, v36
	v_lshl_add_u64 v[0:1], v[8:9], 0, v[28:29]
	v_lshl_add_u64 v[4:5], v[10:11], 0, v[28:29]
	v_lshl_add_u64 v[8:9], v[8:9], 0, v[32:33]
	v_lshl_add_u64 v[12:13], v[10:11], 0, v[32:33]
	v_lshl_add_u64 v[20:21], v[36:37], 1, v[16:17]
	global_load_dwordx4 v[0:3], v[0:1], off nt
	s_nop 0
	global_load_dwordx4 v[4:7], v[4:5], off nt
	s_nop 0
	global_load_dwordx4 v[8:11], v[8:9], off nt
	s_nop 0
	global_load_dwordx4 v[12:15], v[12:13], off nt
	s_nop 0
	global_load_dwordx4 v[16:19], v[20:21], off nt
	s_nop 0
	global_load_dwordx4 v[20:23], v[20:21], off offset:2048 nt
	v_and_b32_e32 v53, 15, v52
	s_movk_i32 s0, 0xa0
	v_lshlrev_b32_e32 v62, 4, v71
	v_lshlrev_b64 v[56:57], 10, v[30:31]
	v_cmp_gt_i32_e64 s[38:39], s0, v52
	v_add_u32_e32 v25, -16, v52
	s_movk_i32 s0, 0x81
	v_or_b32_e32 v44, v62, v53
	v_and_b32_e32 v31, 48, v52
	v_add_u32_e32 v78, 2, v71
	v_add_u32_e32 v85, 4, v71
	v_add_u32_e32 v92, 6, v71
	v_lshl_add_u32 v38, v39, 2, 0
	v_cmp_gt_u32_e64 s[40:41], s0, v25
	s_movk_i32 s0, 0x1080
	v_add_u32_e32 v46, 0, v31
	v_ashrrev_i32_e32 v45, 31, v44
	v_add_u32_e32 v63, 1, v71
	v_lshlrev_b32_e32 v64, 4, v78
	v_add_u32_e32 v65, 3, v71
	v_lshlrev_b32_e32 v66, 4, v85
	v_add_u32_e32 v67, 5, v71
	v_lshlrev_b32_e32 v68, 4, v92
	v_add_u32_e32 v69, 7, v71
	v_add_u32_e32 v99, 8, v71
	v_bfe_u32 v35, v52, 4, 2
	v_lshlrev_b32_e32 v34, 11, v122
	v_readlane_b32 s34, v250, 5
	v_add_u32_e32 v40, 0, v112
	v_lshlrev_b32_e32 v42, 2, v122
	v_mad_u32_u24 v42, v123, s0, v42
	v_mad_u64_u32 v[48:49], s[0:1], v44, s25, v[46:47]
	v_lshlrev_b64 v[50:51], 11, v[44:45]
	v_cmp_gt_u32_e64 s[42:43], 16, v39
	v_ashrrev_i32_e32 v45, 31, v62
	v_mul_lo_u32 v39, v71, s81
	v_lshrrev_b32_e32 v61, 3, v71
	v_and_b32_e32 v106, 0x70, v62
	v_lshrrev_b32_e32 v62, 3, v63
	v_lshlrev_b32_e32 v107, 4, v63
	v_lshrrev_b32_e32 v63, 3, v78
	v_and_b32_e32 v108, 0x70, v64
	v_lshrrev_b32_e32 v64, 3, v65
	v_lshlrev_b32_e32 v109, 4, v65
	v_lshrrev_b32_e32 v65, 3, v85
	v_and_b32_e32 v111, 0x70, v66
	v_lshrrev_b32_e32 v66, 3, v67
	v_lshlrev_b32_e32 v112, 4, v67
	v_lshrrev_b32_e32 v67, 3, v92
	v_and_b32_e32 v116, 0x70, v68
	v_lshrrev_b32_e32 v68, 3, v69
	v_lshlrev_b32_e32 v117, 4, v69
	v_lshrrev_b32_e32 v69, 3, v99
	v_lshlrev_b32_e32 v70, 4, v99
	v_cmp_lt_i32_e64 s[44:45], 7, v71
	v_cmp_lt_i32_e64 s[54:55], 6, v71
	v_cmp_lt_i32_e64 s[56:57], 5, v71
	v_cmp_lt_i32_e64 s[58:59], 4, v71
	v_cmp_lt_i32_e64 s[60:61], 3, v71
	v_cmp_lt_i32_e64 s[62:63], 2, v71
	v_cmp_lt_i32_e64 s[64:65], 1, v71
	v_cmp_lt_i32_e64 s[66:67], 0, v71
	v_cmp_lt_i32_e64 s[68:69], -1, v71
	v_min_i32_e32 v71, 14, v71
	v_min_i32_e32 v78, 14, v78
	v_min_i32_e32 v85, 14, v85
	v_min_i32_e32 v92, 14, v92
	v_min_i32_e32 v99, 14, v99
	v_lshlrev_b64 v[54:55], 10, v[26:27]
	v_lshl_add_u32 v27, v52, 2, s34
	v_or_b32_e32 v31, 16, v53
	v_lshlrev_b32_e32 v110, 2, v35
	v_add_u32_e32 v43, 0x400, v52
	v_add_u32_e32 v47, 0x600, v52
	v_add_u32_e32 v49, 0x800, v52
	v_add_u32_e32 v58, 0xa00, v52
	v_add_u32_e32 v59, 0xc00, v52
	v_add_u32_e32 v52, 0xe00, v52
	v_add_u32_e32 v73, 1, v71
	v_add_u32_e32 v80, 1, v78
	v_add_u32_e32 v87, 1, v85
	v_add_u32_e32 v94, 1, v92
	v_add_u32_e32 v102, 1, v99
	v_sub_u32_e32 v31, v31, v110
	v_ashrrev_i32_e32 v52, 6, v52
	v_and_b32_e32 v118, 0x70, v70
	v_mad_u32_u24 v101, v53, s81, 0
	v_lshrrev_b32_e32 v71, 3, v73
	v_lshlrev_b32_e32 v73, 5, v73
	v_lshrrev_b32_e32 v78, 3, v80
	v_lshlrev_b32_e32 v80, 5, v80
	v_lshrrev_b32_e32 v85, 3, v87
	v_lshlrev_b32_e32 v87, 5, v87
	v_lshrrev_b32_e32 v92, 3, v94
	v_lshlrev_b32_e32 v94, 5, v94
	v_lshrrev_b32_e32 v99, 3, v102
	v_lshlrev_b32_e32 v102, 5, v102
	v_lshlrev_b32_e32 v105, 3, v35
	v_lshl_add_u32 v31, v31, 2, s34
	v_sub_u32_e32 v72, v53, v110
	v_ashrrev_i32_e32 v41, 6, v41
	v_ashrrev_i32_e32 v43, 6, v43
	v_ashrrev_i32_e32 v47, 6, v47
	v_ashrrev_i32_e32 v49, 6, v49
	v_ashrrev_i32_e32 v58, 6, v58
	v_ashrrev_i32_e32 v59, 6, v59
	v_mul_lo_u32 v60, v52, s81
	v_mul_lo_u32 v52, v26, s25
	v_add_u32_e32 v114, 0xd800, v101
	v_lshlrev_b32_e32 v76, 1, v106
	v_and_b32_e32 v77, 0xe0, v73
	v_add_u32_e32 v103, 0x2100, v101
	v_lshlrev_b32_e32 v83, 1, v108
	s_waitcnt lgkmcnt(0)
; #define LAS __attribute__((address_space(3)))
; DI unsigned pk2(float lo, float hi) { f32x2n v = {lo, hi}; bf16x2n b = __builtin_convertvector(v, bf16x2n); return __builtin_bit_cast(unsigned, b); }
; DI float x16_sum(float x) { const unsigned u = __builtin_bit_cast(unsigned, x); auto r = __builtin_amdgcn_permlane16_swap(u, u, false, false); return __builtin_bit_cast(float, (unsigned)r[0]) + __builtin_bit_cast(float, (unsigned)r[1]); }
; DI void attn_phase(LAS unsigned char* lds, bf16_t* QKV, float* LSE, const float* qg, const float* kg, const float* relb, int G, int bid) {
;     ...
;         for (int i = 0; i < 9; ++i) { const bool tv = (n > 0) || (w + i >= 8);
; #pragma unroll
;             for (int j = 0; j < 4; ++j) { bool valid = tv;
;                 if (i == 0) valid = valid && (dlt - j <= 0);
;                 if (i == 8) valid = valid && (dlt - j >= 0);
;                 const float v = valid ? sc[i][j] + bv[i][j] : -INFINITY; sc[i][j] = v; mx = fmaxf(mx, v); } }
;         mx = x16_max(mx); mx = x32_max(mx);
;         float sum = 0.f;
; #pragma unroll
;         for (int i = 0; i < 9; ++i)
; #pragma unroll
;             for (int j = 0; j < 4; ++j) { const float p = __builtin_amdgcn_exp2f(sc[i][j] - mx); sc[i][j] = p; sum += p; }
;         sum = x16_sum(sum); sum = x32_sum(sum);
;         f32x4 o[4];
; #pragma unroll
;         for (int et = 0; et < 4; ++et) o[et] = (f32x4){0.f, 0.f, 0.f, 0.f};
; #pragma unroll
;         for (int pi = 0; pi < 5; ++pi) { const int ia = 2 * pi, ib = (2 * pi + 1 < 9) ? 2 * pi + 1 : 8;
;             u32x4 pw; pw.x = pk2(sc[ia][0], sc[ia][1]); pw.y = pk2(sc[ia][2], sc[ia][3]);
;             if (2 * pi + 1 < 9) { pw.z = pk2(sc[ib][0], sc[ib][1]); pw.w = pk2(sc[ib][2], sc[ib][3]); } else { pw.z = 0u; pw.w = 0u; }
;             const bf16x8 pb = __builtin_bit_cast(bf16x8, pw);
;             const int ta = w + ia; int tb = w + 2 * pi + 1; if (tb > 15) tb = 15;
;             const int ca = ((((n + 1 + (ta >> 3)) & 1) << 7) | ((ta & 7) << 4)) + 4 * fq, cb = ((((n + 1 + (tb >> 3)) & 1) << 7) | ((tb & 7) << 4)) + 4 * fq;
; #pragma unroll
;             for (int et = 0; et < 4; ++et) { const LAS bf16_t* vr = Vt + (16 * et + fr) * 264;
;                 const u32x2 lo = *(const LAS u32x2*)(vr + ca), hi = *(const LAS u32x2*)(vr + cb);
	v_and_b32_e32 v84, 0xe0, v80
	v_lshlrev_b32_e32 v90, 1, v111
	v_and_b32_e32 v91, 0xe0, v87
	v_lshlrev_b32_e32 v97, 1, v116
	v_and_b32_e32 v98, 0xe0, v94
	v_lshlrev_b32_e32 v104, 1, v118
	v_and_b32_e32 v115, 0xe0, v102
	v_mul_lo_u32 v120, v30, s25
	s_movk_i32 s0, 0x70
	v_add_u32_e32 v35, -12, v31
	v_mul_lo_u32 v41, v41, s81
	v_mul_lo_u32 v43, v43, s81
	v_mul_lo_u32 v47, v47, s81
	v_mul_lo_u32 v49, v49, s81
	v_mul_lo_u32 v58, v58, s81
	v_mul_lo_u32 v59, v59, s81
	v_add_u32_e32 v70, -4, v31
	v_cmp_gt_i32_e64 s[46:47], 1, v72
	v_cmp_gt_i32_e64 s[48:49], 2, v72
	v_cmp_gt_i32_e64 s[50:51], 3, v72
	v_cmp_gt_i32_e64 s[52:53], 4, v72
	s_mov_b32 s87, 0
	v_cmp_lt_i32_e64 s[70:71], -1, v72
	v_cmp_lt_i32_e64 s[72:73], 0, v72
	v_cmp_lt_i32_e64 s[74:75], 1, v72
	v_cmp_lt_i32_e64 s[76:77], 2, v72
	v_add3_u32 v72, v101, v76, v105
	v_add3_u32 v73, v101, v77, v105
	v_add3_u32 v74, v103, v76, v105
	v_add3_u32 v75, v103, v77, v105
	v_add3_u32 v76, v114, v76, v105
	v_add3_u32 v77, v114, v77, v105
	v_add3_u32 v79, v101, v83, v105
	v_add3_u32 v80, v101, v84, v105
	v_add3_u32 v81, v103, v83, v105
	v_add3_u32 v82, v103, v84, v105
	v_add3_u32 v83, v114, v83, v105
	v_add3_u32 v84, v114, v84, v105
	v_add3_u32 v86, v101, v90, v105
	v_add3_u32 v87, v101, v91, v105
	v_add3_u32 v88, v103, v90, v105
	v_add3_u32 v89, v103, v91, v105
	v_add3_u32 v90, v114, v90, v105
	v_add3_u32 v91, v114, v91, v105
	v_add3_u32 v93, v101, v97, v105
	v_add3_u32 v94, v101, v98, v105
	v_add3_u32 v95, v103, v97, v105
	v_add3_u32 v96, v103, v98, v105
	v_add3_u32 v97, v114, v97, v105
	v_add3_u32 v98, v114, v98, v105
	v_add3_u32 v100, v101, v104, v105
	v_add3_u32 v101, v101, v115, v105
	v_add3_u32 v102, v103, v104, v105
	v_add3_u32 v103, v103, v115, v105
	v_add3_u32 v104, v114, v104, v105
	v_add3_u32 v105, v114, v115, v105
	v_or_b32_e32 v106, v106, v53
	v_and_or_b32 v107, v107, s0, v53
	v_or_b32_e32 v108, v108, v53
	v_and_or_b32 v109, v109, s0, v53
	v_or_b32_e32 v114, v111, v53
	v_and_or_b32 v115, v112, s0, v53
	v_or_b32_e32 v116, v116, v53
	v_and_or_b32 v117, v117, s0, v53
	v_or_b32_e32 v118, v118, v53
	v_add_u32_e32 v119, v40, v52
	v_add_u32_e32 v120, v40, v120
	v_lshlrev_b64 v[52:53], 1, v[54:55]
	v_lshlrev_b64 v[54:55], 1, v[56:57]
	v_lshlrev_b32_e32 v56, 1, v110
	v_readlane_b32 s78, v251, 27
	s_branch .LBB0_314

; #define LAS __attribute__((address_space(3)))
; DI void lbar() { asm volatile("s_waitcnt lgkmcnt(0)" ::: "memory"); __builtin_amdgcn_s_barrier(); asm volatile("" ::: "memory"); }
; DI void attn_phase(LAS unsigned char* lds, bf16_t* QKV, float* LSE, const float* qg, const float* kg, const float* relb, int G, int bid) {
;     ...
;         attn_unit_ptrs(u, rn, h, g, d, n, rowbase);
;         bf16_t* qp = QKV + (size_t)g * SEC + rowbase * 1024 + h * 64;
;         const int slot = n & 1;
;         lbar();
;         if (u == u0 || n == 0) { if (tid < 160) tab[tid] = (tid >= 16 && tid <= 144) ? 1.4426950408889634f * bucket_bias(relb, (tid - 16) * d, g, h) : 0.f; }
;         if (n == 0) {
; #pragma unroll
;             for (int i = 0; i < 8; ++i) { const int idx = tid + 512 * i; Vt32[(idx >> 6) * 132 + (slot ^ 1) * 64 + (idx & 63)] = 0u; }
;         } else if (u == u0) {
;             const bf16_t* kp = qp + 3 * SEC - (size_t)128 * 1024; const bf16_t* vp = qp + 6 * SEC - (size_t)128 * 1024;
; #pragma unroll
;             for (int it = 0; it < 2; ++it) { const int idx = tid + 512 * it, row = idx >> 3, pc = idx & 7;
;                 const u32x4 raw = *(const u32x4*)(kp + (size_t)row * 1024 + pc * 8);
;                 *(LAS u32x4*)(Ks + ((slot ^ 1) * 128 + row) * 72 + pc * 8) = raw; }
;             const u32x4 r0 = *(const u32x4*)(vp + (size_t)(2 * kp2) * 1024 + vpc * 8), r1 = *(const u32x4*)(vp + (size_t)(2 * kp2 + 1) * 1024 + vpc * 8);
;             vt_store(Vt32 + (8 * vpc) * 132 + (slot ^ 1) * 64 + kp2, r0, r1);
.LBB0_320:
	s_or_b64 exec, exec, s[94:95]
	s_mul_hi_i32 s82, s2, 0x2aaaaaab
	s_lshr_b32 s83, s82, 31
	s_lshr_b32 s82, s82, 9
	s_add_i32 s82, s82, s83
	s_lshl_b32 s82, s82, 13
	s_and_b32 s83, s78, 0x1f80
	s_or_b32 s94, s83, s82
	s_ashr_i32 s95, s94, 31
	s_lshl_b64 s[82:83], s[0:1], 25
	s_add_u32 s90, s28, s82
	s_addc_u32 s91, s29, s83
	s_lshl_b64 s[82:83], s[94:95], 11
	s_add_u32 s82, s90, s82
	s_addc_u32 s83, s91, s83
	s_lshl_b32 s90, s34, 7
	s_add_u32 s96, s82, s90
	s_addc_u32 s97, s83, 0
	s_and_b32 s82, s2, 1
	s_mov_b64 s[90:91], -1
	s_and_b64 vcc, exec, s[88:89]
	s_cbranch_vccz .LBB0_324
	s_andn2_b64 vcc, exec, s[98:99]
	s_cbranch_vccnz .LBB0_323
	v_lshlrev_b32_e32 v112, 1, v24
	v_lshl_add_u64 v[110:111], s[96:97], 0, v[112:113]
	s_mov_b64 s[88:89], 0x5fc0000
	v_lshl_add_u64 v[110:111], v[110:111], 0, s[88:89]
	v_lshl_add_u64 v[122:123], v[110:111], 0, v[28:29]
	global_load_dwordx4 v[122:125], v[122:123], off nt
	s_lshl_b32 s83, s82, 7
	s_xor_b32 s83, s83, 0x80
	v_add_u32_e32 v57, s83, v26
	v_mad_u64_u32 v[126:127], s[88:89], v57, s25, v[40:41]
	v_lshl_add_u64 v[110:111], v[110:111], 0, v[32:33]
	v_add_u32_e32 v57, s83, v30
	v_lshlrev_b32_e32 v112, 1, v34
	s_mov_b32 s83, 0xbfc0000
	s_waitcnt vmcnt(0)
	ds_write_b128 v126, v[122:125] offset:18432
	global_load_dwordx4 v[122:125], v[110:111], off nt
	v_mad_u64_u32 v[110:111], s[88:89], v57, s25, v[40:41]
	s_mov_b64 s[88:89], 0xbfc0000
	s_waitcnt vmcnt(0)
	ds_write_b128 v110, v[122:125] offset:18432
	v_lshl_add_u64 v[110:111], s[96:97], 0, v[112:113]
	v_lshl_add_u64 v[110:111], v[36:37], 1, v[110:111]
	v_lshl_add_u64 v[126:127], v[110:111], 0, s[88:89]
	v_add_co_u32_e32 v110, vcc, s83, v110
	s_lshl_b32 s83, s82, 8
	s_nop 0
	v_addc_co_u32_e32 v111, vcc, 0, v111, vcc
	global_load_dwordx4 v[122:125], v[110:111], off nt
	s_nop 0
	global_load_dwordx4 v[126:129], v[126:127], off offset:2048 nt
	s_xor_b32 s83, s83, 0x100
	v_add_u32_e32 v57, s83, v42
	v_add_u32_e32 v112, 0xd800, v57
	s_waitcnt vmcnt(1)
	v_and_b32_e32 v110, 0xffff, v122
	v_lshrrev_b32_e32 v111, 16, v122
	s_waitcnt vmcnt(0)
	v_lshl_or_b32 v110, v126, 16, v110
	v_and_or_b32 v111, v126, s27, v111
	ds_write2_b32 v112, v110, v111 offset1:132
	v_and_b32_e32 v110, 0xffff, v123
	v_lshrrev_b32_e32 v111, 16, v123
	v_lshl_or_b32 v110, v127, 16, v110
	v_and_or_b32 v111, v127, s27, v111
	v_add_u32_e32 v112, 0xdc00, v57
	ds_write2_b32 v112, v110, v111 offset0:8 offset1:140
	v_and_b32_e32 v110, 0xffff, v124
	v_lshrrev_b32_e32 v111, 16, v124
	v_lshl_or_b32 v110, v128, 16, v110
	v_and_or_b32 v111, v128, s27, v111
	v_add_u32_e32 v112, 0xe000, v57
	ds_write2_b32 v112, v110, v111 offset0:16 offset1:148
	v_and_b32_e32 v110, 0xffff, v125
	v_lshrrev_b32_e32 v111, 16, v125
	v_lshl_or_b32 v110, v129, 16, v110
	v_and_or_b32 v111, v129, s27, v111
	v_add_u32_e32 v57, 0xe400, v57
	ds_write2_b32 v57, v110, v111 offset0:24 offset1:156

; DI void lbar() { asm volatile("s_waitcnt lgkmcnt(0)" ::: "memory"); __builtin_amdgcn_s_barrier(); asm volatile("" ::: "memory"); }
; DI void attn_phase(LAS unsigned char* lds, bf16_t* QKV, float* LSE, const float* qg, const float* kg, const float* relb, int G, int bid) {
;     ...
;         vt_store(Vt32 + (8 * vpc) * 132 + slot * 64 + kp2, pv[0], pv[1]);
;         lbar();
;         if (u + 1 < u1) {
;             int rn2, h2, g2, d2, n2; size_t rb2; attn_unit_ptrs(u + 1, rn2, h2, g2, d2, n2, rb2);
;             const bf16_t* qp2 = QKV + (size_t)g2 * SEC + rb2 * 1024 + h2 * 64; const bf16_t* kp2p = qp2 + 3 * SEC; const bf16_t* vp2 = qp2 + 6 * SEC;
; #pragma unroll
;             for (int it = 0; it < 2; ++it) { const int idx = tid + 512 * it, row = idx >> 3, pc = idx & 7; pq[it] = *(const u32x4*)(qp2 + (size_t)row * 1024 + pc * 8); pk[it] = *(const u32x4*)(kp2p + (size_t)row * 1024 + pc * 8); }
;             pv[0] = *(const u32x4*)(vp2 + (size_t)(2 * kp2) * 1024 + vpc * 8); pv[1] = *(const u32x4*)(vp2 + (size_t)(2 * kp2 + 1) * 1024 + vpc * 8);
;         }
.Lat_join:
	v_lshlrev_b32_e32 v110, 16, v20
	s_mov_b32 s82, 0xffff
	v_lshrrev_b32_e32 v111, 16, v16
	v_and_or_b32 v110, v16, s82, v110
	v_and_or_b32 v111, v20, s27, v111
	v_add_u32_e32 v112, 0xd800, v57
	ds_write2_b32 v112, v110, v111 offset1:132
	v_lshlrev_b32_e32 v110, 16, v21
	v_lshrrev_b32_e32 v111, 16, v17
	v_and_or_b32 v110, v17, s82, v110
	v_and_or_b32 v111, v21, s27, v111
	v_add_u32_e32 v112, 0xdc00, v57
	ds_write2_b32 v112, v110, v111 offset0:8 offset1:140
	v_lshlrev_b32_e32 v110, 16, v22
	v_lshrrev_b32_e32 v111, 16, v18
	v_and_or_b32 v110, v18, s82, v110
	v_and_or_b32 v111, v22, s27, v111
	v_add_u32_e32 v112, 0xe000, v57
	ds_write2_b32 v112, v110, v111 offset0:16 offset1:148
	v_lshlrev_b32_e32 v110, 16, v23
	v_lshrrev_b32_e32 v111, 16, v19
	v_and_or_b32 v110, v19, s82, v110
	v_and_or_b32 v111, v23, s27, v111
	v_add_u32_e32 v57, 0xe400, v57
	ds_write2_b32 v57, v110, v111 offset0:24 offset1:156
	s_waitcnt lgkmcnt(0)
	s_barrier
	s_add_i32 s2, s2, 1
	v_readlane_b32 s82, v251, 24
	s_cmp_ge_i32 s2, s82
	s_cbranch_scc1 .LBB0_328
	s_ashr_i32 s82, s2, 10
	s_mul_hi_i32 s83, s82, 0x55555556
	s_lshr_b32 s88, s83, 31
	s_add_i32 s83, s83, s88
	s_and_b32 s90, s2, 0x3c0
	s_mul_i32 s83, s83, 3
	s_mul_hi_i32 s2, s2, 0x2aaaaaab
	s_sub_i32 s82, s82, s83
	s_lshr_b32 s83, s2, 31
	s_lshr_b32 s2, s2, 9
	s_add_i32 s2, s2, s83
	s_add_i32 s83, s78, 0x80
	s_lshl_b32 s2, s2, 13
	s_and_b32 s83, s83, 0x1f80
	s_or_b32 s88, s83, s2
	s_ashr_i32 s83, s82, 31
	s_ashr_i32 s89, s88, 31
	s_lshl_b64 s[82:83], s[82:83], 25
	s_add_u32 s2, s28, s82
	s_addc_u32 s91, s29, s83
	s_lshl_b64 s[82:83], s[88:89], 11
	s_add_u32 s2, s2, s82
	s_addc_u32 s83, s91, s83
	s_lshl_b32 s82, s90, 1
	s_add_u32 s82, s2, s82
	s_addc_u32 s83, s83, 0
	v_lshlrev_b32_e32 v112, 1, v24
	v_lshl_add_u64 v[8:9], s[82:83], 0, v[112:113]
	v_lshlrev_b32_e32 v112, 1, v34
	v_lshl_add_u64 v[16:17], s[82:83], 0, v[112:113]
	s_mov_b64 s[88:89], 0x6000000
	v_lshl_add_u64 v[16:17], v[36:37], 1, v[16:17]
	s_mov_b64 s[82:83], 0xc000000
	v_lshl_add_u64 v[10:11], v[8:9], 0, s[88:89]
	v_lshl_add_u64 v[20:21], v[16:17], 0, s[82:83]
	v_add_co_u32_e32 v16, vcc, 0xc000000, v16
	v_lshl_add_u64 v[0:1], v[8:9], 0, v[52:53]
	v_lshl_add_u64 v[4:5], v[10:11], 0, v[52:53]
	v_lshl_add_u64 v[8:9], v[8:9], 0, v[54:55]
	v_lshl_add_u64 v[12:13], v[10:11], 0, v[54:55]
	v_addc_co_u32_e32 v17, vcc, 0, v17, vcc
	global_load_dwordx4 v[0:3], v[0:1], off nt
	s_nop 0
	global_load_dwordx4 v[4:7], v[4:5], off nt
	s_nop 0
	global_load_dwordx4 v[8:11], v[8:9], off nt
	s_nop 0
	global_load_dwordx4 v[12:15], v[12:13], off nt
	s_nop 0
	global_load_dwordx4 v[16:19], v[16:17], off nt
	s_nop 0
	global_load_dwordx4 v[20:23], v[20:21], off offset:2048 nt
